# hand-written software-pipelined weight conversion (next item's loads in flight during the LDS transpose) at the up-front, gi0-tail and gi6-tail sites
# speedup vs baseline: 1.0057x; 1.0057x over previous
.LBB0_33:
	s_or_b64 exec, exec, s[2:3]
	v_mov_b32_e32 v1, s64
	v_mov_b32_e32 v2, s65
	v_writelane_b32 v253, s64, 2
	v_readfirstlane_b32 s2, v1
	v_readfirstlane_b32 s3, v2
	v_mov_b32_e32 v1, s88
	v_mov_b32_e32 v2, s2
	v_mov_b32_e32 v3, s3
	global_load_dwordx2 v[2:3], v[2:3], off offset:248
	v_writelane_b32 v253, s65, 3
	s_waitcnt vmcnt(0) lgkmcnt(0)
	v_writelane_b32 v253, s60, 4
	v_readfirstlane_b32 s39, v1
	v_readfirstlane_b32 s38, v2
	s_cmpk_gt_u32 s39, 0x65f
	v_readfirstlane_b32 s40, v3
	v_writelane_b32 v253, s61, 5
	s_cbranch_scc1 .LBB0_345
	s_mov_b32 s89, 0
	s_movk_i32 s90, 0x660
	s_mov_b32 s91, 0
	s_mov_b32 s92, 0
	s_mov_b32 s101, 1
	s_branch .Lcv1_entry
	s_add_u32 s41, s38, 0x2d80000
	s_addc_u32 s42, s40, 0
	s_add_u32 s43, s38, 0x2280000
	s_addc_u32 s44, s40, 0
	s_add_u32 s45, s38, 0x2080000
	s_addc_u32 s46, s40, 0
	s_add_u32 s47, s38, 0x1e80000
	s_addc_u32 s48, s40, 0
	s_add_u32 s49, s38, 0x1080000
	s_addc_u32 s50, s40, 0
	s_add_u32 s51, s38, 0xb00000
	v_readlane_b32 s2, v253, 0
	s_mov_b64 s[90:91], s[62:63]
	s_addc_u32 s52, s40, 0
	s_lshl_b32 s53, s39, 8
	s_lshl_b32 s54, s2, 8
	s_lshl_b32 s55, s39, 4
	s_lshl_b32 s56, s2, 4
	s_movk_i32 s57, 0x4ff
	s_mov_b32 s5, 0
	v_mov_b32_e32 v35, 0
	s_movk_i32 s58, 0x104
	s_movk_i32 s59, 0x400
	s_movk_i32 s60, 0x1600
	s_movk_i32 s61, 0x2c00
	s_movk_i32 s62, 0xb00
	s_movk_i32 s63, 0x1f00
	s_movk_i32 s64, 0x6c20
	s_movk_i32 s65, 0x1b09
	s_movk_i32 s66, 0x1b08
	s_movk_i32 s67, 0x17f
	s_movk_i32 s68, 0x1ff
	s_movk_i32 s69, 0x2ff
	s_movk_i32 s70, 0x3ff
	s_movk_i32 s71, 0x5ff
	s_movk_i32 s72, 0x67f
	s_movk_i32 s73, 0x6ff
	s_movk_i32 s74, 0x7ff
	s_movk_i32 s75, 0x8ff
	s_movk_i32 s76, 0x9ff
	s_movk_i32 s77, 0xaff
	s_movk_i32 s78, 0xb07
	v_readlane_b32 s3, v253, 1
	s_branch .LBB0_37

.Lcv1_entry:
	s_mov_b64 exec, -1
	s_cmp_lt_u32 s88, s91
	s_cbranch_scc1 .Lcv1_ret
	s_sub_u32 s93, s88, s91
	s_add_u32 s93, s93, s89
	s_cmp_ge_u32 s93, s90
	s_cbranch_scc1 .Lcv1_ret
	s_sub_u32 s95, 0x100, s91
	s_load_dwordx2 s[4:5], s[64:65], 0xf8
	s_load_dwordx2 s[6:7], s[64:65], 0x38
	s_load_dwordx2 s[8:9], s[64:65], 0x40
	s_load_dwordx2 s[20:21], s[64:65], 0x48
	s_load_dwordx2 s[34:35], s[64:65], 0x58
	s_load_dwordx2 s[40:41], s[64:65], 0xb8
	s_load_dwordx2 s[42:43], s[64:65], 0xc0
	s_load_dwordx2 s[46:47], s[64:65], 0xd0
	s_load_dwordx2 s[48:49], s[64:65], 0xd8
	s_load_dwordx2 s[50:51], s[64:65], 0xe0
	v_lshrrev_b32_e32 v132, 3, v247
	v_and_b32_e32 v133, 7, v247
	v_lshlrev_b32_e32 v133, 3, v133
	v_mul_u32_u24_e32 v134, 0x41, v132
	v_add_u32_e32 v134, v134, v133
	v_lshl_add_u32 v134, v134, 2, 16
	v_mul_u32_u24_e32 v135, 0x41, v133
	v_add_u32_e32 v135, v135, v132
	v_lshl_add_u32 v135, v135, 2, 16
	s_waitcnt lgkmcnt(0)
	s_barrier
	s_mov_b32 s97, 0
	s_mov_b32 s56, 0
	s_cmp_ge_u32 s93, 176
	s_cselect_b32 s97, 1, s97
	s_cselect_b32 s56, 176, s56
	s_cmp_ge_u32 s93, 352
	s_cselect_b32 s97, 2, s97
	s_cselect_b32 s56, 352, s56
	s_cmp_ge_u32 s93, 528
	s_cselect_b32 s97, 3, s97
	s_cselect_b32 s56, 528, s56
	s_cmp_ge_u32 s93, 976
	s_cselect_b32 s97, 4, s97
	s_cselect_b32 s56, 976, s56
	s_cmp_ge_u32 s93, 1040
	s_cselect_b32 s97, 5, s97
	s_cselect_b32 s56, 1040, s56
	s_cmp_ge_u32 s93, 1104
	s_cselect_b32 s97, 6, s97
	s_cselect_b32 s56, 1104, s56
	s_cmp_ge_u32 s93, 1280
	s_cselect_b32 s97, 7, s97
	s_cselect_b32 s56, 1280, s56
	s_cmp_ge_u32 s93, 1456
	s_cselect_b32 s97, 8, s97
	s_cselect_b32 s56, 1456, s56
	s_sub_u32 s98, s93, s56
	s_and_b32 s56, s98, 15
	s_lshr_b32 s57, s98, 4
	s_cmp_eq_u32 s97, 4
	s_cselect_b32 s99, s57, 0
	s_cselect_b32 s98, s56, s98
	s_movk_i32 s100, 0x400
	s_mov_b32 s18, 4
	s_movk_i32 s57, 0x4000
	s_mov_b32 s58, 16
	s_movk_i32 s59, 0xc3
	s_bitcmp1_b32 s59, s97
	s_cselect_b32 s100, 0xb00, s100
	s_cselect_b32 s18, 11, s18
	s_cselect_b32 s57, 0x1746, s57
	s_cselect_b32 s58, 44, s58
	s_cmp_eq_u32 s97, 3
	s_cselect_b32 s100, 0x1b08, s100
	s_cselect_b32 s18, 28, s18
	s_cselect_b32 s57, 0x925, s57
	s_cselect_b32 s58, 0x6d, s58
	s_mul_i32 s45, s98, s57
	s_lshr_b32 s45, s45, 16
	s_mul_i32 s59, s45, s18
	s_sub_u32 s52, s98, s59
	s_mov_b32 s56, 0xb00000
	s_cmp_eq_u32 s97, 3
	s_cselect_b32 s56, 0x1b08000, s56
	s_cmp_eq_u32 s97, 5
	s_cselect_b32 s56, 0x400000, s56
	s_cmp_eq_u32 s97, 4
	s_cselect_b32 s56, 0x400000, s56
	s_mul_i32 s56, s56, s92
	s_lshl_b32 s59, s99, 20
	s_add_u32 s56, s56, s59
	s_mul_i32 s59, s45, s100
	s_lshl_b32 s59, s59, 8
	s_add_u32 s56, s56, s59
	s_lshl_b32 s59, s52, 10
	s_add_u32 s56, s56, s59
	s_mov_b64 s[78:79], s[6:7]
	s_cmp_eq_u32 s97, 1
	s_cselect_b32 s78, s8, s78
	s_cselect_b32 s79, s9, s79
	s_cmp_eq_u32 s97, 2
	s_cselect_b32 s78, s20, s78
	s_cselect_b32 s79, s21, s79
	s_cmp_eq_u32 s97, 3
	s_cselect_b32 s78, s34, s78
	s_cselect_b32 s79, s35, s79
	s_cmp_eq_u32 s97, 4
	s_cselect_b32 s78, s40, s78
	s_cselect_b32 s79, s41, s79
	s_cmp_eq_u32 s97, 5
	s_cselect_b32 s78, s42, s78
	s_cselect_b32 s79, s43, s79
	s_cmp_eq_u32 s97, 6
	s_cselect_b32 s78, s46, s78
	s_cselect_b32 s79, s47, s79
	s_cmp_eq_u32 s97, 7
	s_cselect_b32 s78, s48, s78
	s_cselect_b32 s79, s49, s79
	s_cmp_eq_u32 s97, 8
	s_cselect_b32 s78, s50, s78
	s_cselect_b32 s79, s51, s79
	s_add_u32 s78, s78, s56
	s_addc_u32 s79, s79, 0
	s_lshl_b32 s59, s100, 2
	v_mul_u32_u24_e32 v141, s59, v132
	v_lshl_add_u32 v141, v133, 2, v141
	s_lshl_b32 s80, s52, 2
	s_cmp_lt_u32 s80, s58
	s_cselect_b32 s81, 0, 0
	s_lshl_b32 s80, s52, 8
	s_add_u32 s80, s80, s81
	s_sub_i32 s80, s100, s80
	s_sub_i32 s80, s80, 8
	v_cmp_ge_i32_e32 vcc, s80, v133
	s_mov_b64 exec, vcc
	s_lshl_b32 s81, s81, 2
	s_add_u32 s56, s78, s81
	s_addc_u32 s57, s79, 0
	global_load_dwordx4 v[100:103], v141, s[56:57]
	global_load_dwordx4 v[104:107], v141, s[56:57] offset:16
	s_lshl_b32 s80, s52, 2
	s_add_u32 s80, s80, 1
	s_cmp_lt_u32 s80, s58
	s_cselect_b32 s81, 64, 0
	s_lshl_b32 s80, s52, 8
	s_add_u32 s80, s80, s81
	s_sub_i32 s80, s100, s80
	s_sub_i32 s80, s80, 8
	v_cmp_ge_i32_e32 vcc, s80, v133
	s_mov_b64 exec, vcc
	s_lshl_b32 s81, s81, 2
	s_add_u32 s56, s78, s81
	s_addc_u32 s57, s79, 0
	global_load_dwordx4 v[108:111], v141, s[56:57]
	global_load_dwordx4 v[112:115], v141, s[56:57] offset:16
	s_lshl_b32 s80, s52, 2
	s_add_u32 s80, s80, 2
	s_cmp_lt_u32 s80, s58
	s_cselect_b32 s81, 128, 0
	s_lshl_b32 s80, s52, 8
	s_add_u32 s80, s80, s81
	s_sub_i32 s80, s100, s80
	s_sub_i32 s80, s80, 8
	v_cmp_ge_i32_e32 vcc, s80, v133
	s_mov_b64 exec, vcc
	s_lshl_b32 s81, s81, 2
	s_add_u32 s56, s78, s81
	s_addc_u32 s57, s79, 0
	global_load_dwordx4 v[116:119], v141, s[56:57]
	global_load_dwordx4 v[120:123], v141, s[56:57] offset:16
	s_lshl_b32 s80, s52, 2
	s_add_u32 s80, s80, 3
	s_cmp_lt_u32 s80, s58
	s_cselect_b32 s81, 192, 0
	s_lshl_b32 s80, s52, 8
	s_add_u32 s80, s80, s81
	s_sub_i32 s80, s100, s80
	s_sub_i32 s80, s80, 8
	v_cmp_ge_i32_e32 vcc, s80, v133
	s_mov_b64 exec, vcc
	s_lshl_b32 s81, s81, 2
	s_add_u32 s56, s78, s81
	s_addc_u32 s57, s79, 0
	global_load_dwordx4 v[124:127], v141, s[56:57]
	global_load_dwordx4 v[128:131], v141, s[56:57] offset:16
	s_mov_b64 exec, -1
.Lcv1_loop:
	s_add_u32 s96, s93, s95
	s_cmp_lt_u32 s96, s90
	s_cbranch_scc0 .Lcv1_last0
	s_mov_b32 s97, 0
	s_mov_b32 s56, 0
	s_cmp_ge_u32 s96, 176
	s_cselect_b32 s97, 1, s97
	s_cselect_b32 s56, 176, s56
	s_cmp_ge_u32 s96, 352
	s_cselect_b32 s97, 2, s97
	s_cselect_b32 s56, 352, s56
	s_cmp_ge_u32 s96, 528
	s_cselect_b32 s97, 3, s97
	s_cselect_b32 s56, 528, s56
	s_cmp_ge_u32 s96, 976
	s_cselect_b32 s97, 4, s97
	s_cselect_b32 s56, 976, s56
	s_cmp_ge_u32 s96, 1040
	s_cselect_b32 s97, 5, s97
	s_cselect_b32 s56, 1040, s56
	s_cmp_ge_u32 s96, 1104
	s_cselect_b32 s97, 6, s97
	s_cselect_b32 s56, 1104, s56
	s_cmp_ge_u32 s96, 1280
	s_cselect_b32 s97, 7, s97
	s_cselect_b32 s56, 1280, s56
	s_cmp_ge_u32 s96, 1456
	s_cselect_b32 s97, 8, s97
	s_cselect_b32 s56, 1456, s56
	s_sub_u32 s98, s96, s56
	s_and_b32 s56, s98, 15
	s_lshr_b32 s57, s98, 4
	s_cmp_eq_u32 s97, 4
	s_cselect_b32 s99, s57, 0
	s_cselect_b32 s98, s56, s98
	s_movk_i32 s100, 0x400
	s_mov_b32 s18, 4
	s_movk_i32 s57, 0x4000
	s_mov_b32 s58, 16
	s_movk_i32 s59, 0xc3
	s_bitcmp1_b32 s59, s97
	s_cselect_b32 s100, 0xb00, s100
	s_cselect_b32 s18, 11, s18
	s_cselect_b32 s57, 0x1746, s57
	s_cselect_b32 s58, 44, s58
	s_cmp_eq_u32 s97, 3
	s_cselect_b32 s100, 0x1b08, s100
	s_cselect_b32 s18, 28, s18
	s_cselect_b32 s57, 0x925, s57
	s_cselect_b32 s58, 0x6d, s58
	s_mul_i32 s45, s98, s57
	s_lshr_b32 s45, s45, 16
	s_mul_i32 s59, s45, s18
	s_sub_u32 s52, s98, s59
	s_mov_b32 s56, 0xb00000
	s_cmp_eq_u32 s97, 3
	s_cselect_b32 s56, 0x1b08000, s56
	s_cmp_eq_u32 s97, 5
	s_cselect_b32 s56, 0x400000, s56
	s_cmp_eq_u32 s97, 4
	s_cselect_b32 s56, 0x400000, s56
	s_mul_i32 s56, s56, s92
	s_lshl_b32 s59, s99, 20
	s_add_u32 s56, s56, s59
	s_mul_i32 s59, s45, s100
	s_lshl_b32 s59, s59, 8
	s_add_u32 s56, s56, s59
	s_lshl_b32 s59, s52, 10
	s_add_u32 s56, s56, s59
	s_mov_b64 s[78:79], s[6:7]
	s_cmp_eq_u32 s97, 1
	s_cselect_b32 s78, s8, s78
	s_cselect_b32 s79, s9, s79
	s_cmp_eq_u32 s97, 2
	s_cselect_b32 s78, s20, s78
	s_cselect_b32 s79, s21, s79
	s_cmp_eq_u32 s97, 3
	s_cselect_b32 s78, s34, s78
	s_cselect_b32 s79, s35, s79
	s_cmp_eq_u32 s97, 4
	s_cselect_b32 s78, s40, s78
	s_cselect_b32 s79, s41, s79
	s_cmp_eq_u32 s97, 5
	s_cselect_b32 s78, s42, s78
	s_cselect_b32 s79, s43, s79
	s_cmp_eq_u32 s97, 6
	s_cselect_b32 s78, s46, s78
	s_cselect_b32 s79, s47, s79
	s_cmp_eq_u32 s97, 7
	s_cselect_b32 s78, s48, s78
	s_cselect_b32 s79, s49, s79
	s_cmp_eq_u32 s97, 8
	s_cselect_b32 s78, s50, s78
	s_cselect_b32 s79, s51, s79
	s_add_u32 s78, s78, s56
	s_addc_u32 s79, s79, 0
	s_lshl_b32 s59, s100, 2
	v_mul_u32_u24_e32 v141, s59, v132
	v_lshl_add_u32 v141, v133, 2, v141
	s_lshl_b32 s80, s52, 2
	s_cmp_lt_u32 s80, s58
	s_cselect_b32 s81, 0, 0
	s_lshl_b32 s80, s52, 8
	s_add_u32 s80, s80, s81
	s_sub_i32 s80, s100, s80
	s_sub_i32 s80, s80, 8
	v_cmp_ge_i32_e32 vcc, s80, v133
	s_mov_b64 exec, vcc
	s_lshl_b32 s81, s81, 2
	s_add_u32 s56, s78, s81
	s_addc_u32 s57, s79, 0
	global_load_dwordx4 v[168:171], v141, s[56:57]
	global_load_dwordx4 v[172:175], v141, s[56:57] offset:16
	s_lshl_b32 s80, s52, 2
	s_add_u32 s80, s80, 1
	s_cmp_lt_u32 s80, s58
	s_cselect_b32 s81, 64, 0
	s_lshl_b32 s80, s52, 8
	s_add_u32 s80, s80, s81
	s_sub_i32 s80, s100, s80
	s_sub_i32 s80, s80, 8
	v_cmp_ge_i32_e32 vcc, s80, v133
	s_mov_b64 exec, vcc
	s_lshl_b32 s81, s81, 2
	s_add_u32 s56, s78, s81
	s_addc_u32 s57, s79, 0
	global_load_dwordx4 v[176:179], v141, s[56:57]
	global_load_dwordx4 v[180:183], v141, s[56:57] offset:16
	s_lshl_b32 s80, s52, 2
	s_add_u32 s80, s80, 2
	s_cmp_lt_u32 s80, s58
	s_cselect_b32 s81, 128, 0
	s_lshl_b32 s80, s52, 8
	s_add_u32 s80, s80, s81
	s_sub_i32 s80, s100, s80
	s_sub_i32 s80, s80, 8
	v_cmp_ge_i32_e32 vcc, s80, v133
	s_mov_b64 exec, vcc
	s_lshl_b32 s81, s81, 2
	s_add_u32 s56, s78, s81
	s_addc_u32 s57, s79, 0
	global_load_dwordx4 v[184:187], v141, s[56:57]
	global_load_dwordx4 v[188:191], v141, s[56:57] offset:16
	s_lshl_b32 s80, s52, 2
	s_add_u32 s80, s80, 3
	s_cmp_lt_u32 s80, s58
	s_cselect_b32 s81, 192, 0
	s_lshl_b32 s80, s52, 8
	s_add_u32 s80, s80, s81
	s_sub_i32 s80, s100, s80
	s_sub_i32 s80, s80, 8
	v_cmp_ge_i32_e32 vcc, s80, v133
	s_mov_b64 exec, vcc
	s_lshl_b32 s81, s81, 2
	s_add_u32 s56, s78, s81
	s_addc_u32 s57, s79, 0
	global_load_dwordx4 v[192:195], v141, s[56:57]
	global_load_dwordx4 v[196:199], v141, s[56:57] offset:16
	s_mov_b64 exec, -1
	s_waitcnt vmcnt(8)
	s_branch .Lcv1_go0

.Lcv1_go0:
	ds_write_b32 v134, v100 offset:0
	ds_write_b32 v134, v101 offset:4
	ds_write_b32 v134, v102 offset:8
	ds_write_b32 v134, v103 offset:12
	ds_write_b32 v134, v104 offset:16
	ds_write_b32 v134, v105 offset:20
	ds_write_b32 v134, v106 offset:24
	ds_write_b32 v134, v107 offset:28
	ds_write_b32 v134, v108 offset:16640
	ds_write_b32 v134, v109 offset:16644
	ds_write_b32 v134, v110 offset:16648
	ds_write_b32 v134, v111 offset:16652
	ds_write_b32 v134, v112 offset:16656
	ds_write_b32 v134, v113 offset:16660
	ds_write_b32 v134, v114 offset:16664
	ds_write_b32 v134, v115 offset:16668
	ds_write_b32 v134, v116 offset:33280
	ds_write_b32 v134, v117 offset:33284
	ds_write_b32 v134, v118 offset:33288
	ds_write_b32 v134, v119 offset:33292
	ds_write_b32 v134, v120 offset:33296
	ds_write_b32 v134, v121 offset:33300
	ds_write_b32 v134, v122 offset:33304
	ds_write_b32 v134, v123 offset:33308
	ds_write_b32 v134, v124 offset:49920
	ds_write_b32 v134, v125 offset:49924
	ds_write_b32 v134, v126 offset:49928
	ds_write_b32 v134, v127 offset:49932
	ds_write_b32 v134, v128 offset:49936
	ds_write_b32 v134, v129 offset:49940
	ds_write_b32 v134, v130 offset:49944
	ds_write_b32 v134, v131 offset:49948
	s_mov_b32 s97, 0
	s_mov_b32 s56, 0
	s_cmp_ge_u32 s93, 176
	s_cselect_b32 s97, 1, s97
	s_cselect_b32 s56, 176, s56
	s_cmp_ge_u32 s93, 352
	s_cselect_b32 s97, 2, s97
	s_cselect_b32 s56, 352, s56
	s_cmp_ge_u32 s93, 528
	s_cselect_b32 s97, 3, s97
	s_cselect_b32 s56, 528, s56
	s_cmp_ge_u32 s93, 976
	s_cselect_b32 s97, 4, s97
	s_cselect_b32 s56, 976, s56
	s_cmp_ge_u32 s93, 1040
	s_cselect_b32 s97, 5, s97
	s_cselect_b32 s56, 1040, s56
	s_cmp_ge_u32 s93, 1104
	s_cselect_b32 s97, 6, s97
	s_cselect_b32 s56, 1104, s56
	s_cmp_ge_u32 s93, 1280
	s_cselect_b32 s97, 7, s97
	s_cselect_b32 s56, 1280, s56
	s_cmp_ge_u32 s93, 1456
	s_cselect_b32 s97, 8, s97
	s_cselect_b32 s56, 1456, s56
	s_sub_u32 s98, s93, s56
	s_and_b32 s56, s98, 15
	s_lshr_b32 s57, s98, 4
	s_cmp_eq_u32 s97, 4
	s_cselect_b32 s99, s57, 0
	s_cselect_b32 s98, s56, s98
	s_movk_i32 s100, 0x400
	s_mov_b32 s18, 4
	s_movk_i32 s57, 0x4000
	s_mov_b32 s58, 16
	s_movk_i32 s59, 0xc3
	s_bitcmp1_b32 s59, s97
	s_cselect_b32 s100, 0xb00, s100
	s_cselect_b32 s18, 11, s18
	s_cselect_b32 s57, 0x1746, s57
	s_cselect_b32 s58, 44, s58
	s_cmp_eq_u32 s97, 3
	s_cselect_b32 s100, 0x1b08, s100
	s_cselect_b32 s18, 28, s18
	s_cselect_b32 s57, 0x925, s57
	s_cselect_b32 s58, 0x6d, s58
	s_mul_i32 s45, s98, s57
	s_lshr_b32 s45, s45, 16
	s_mul_i32 s59, s45, s18
	s_sub_u32 s52, s98, s59
	s_mov_b32 s56, 0
	s_movk_i32 s59, 0x41
	s_bitcmp1_b32 s59, s97
	s_cselect_b32 s56, 1, s56
	s_movk_i32 s59, 0x82
	s_bitcmp1_b32 s59, s97
	s_cselect_b32 s56, 2, s56
	s_cmp_eq_u32 s97, 3
	s_cselect_b32 s56, 3, s56
	s_movk_i32 s57, 0x800
	s_movk_i32 s59, 0x104
	s_bitcmp1_b32 s59, s97
	s_cselect_b32 s57, 0x1600, s57
	s_mov_b32 s59, 0
	s_cmp_eq_u32 s97, 2
	s_cselect_b32 s59, 0xb00000, s59
	s_cmp_eq_u32 s97, 3
	s_cselect_b32 s59, 0x1080000, s59
	s_cmp_eq_u32 s97, 4
	s_cselect_b32 s59, 0x1e80000, s59
	s_cmp_eq_u32 s97, 5
	s_cselect_b32 s59, 0x2080000, s59
	s_cmp_eq_u32 s97, 6
	s_cselect_b32 s59, 0x2280000, s59
	s_cmp_eq_u32 s97, 7
	s_cselect_b32 s59, 0x2280000, s59
	s_cmp_eq_u32 s97, 8
	s_cselect_b32 s59, 0x2d80000, s59
	s_lshl_b32 s78, s99, 9
	s_add_u32 s59, s59, s78
	s_lshl_b32 s78, s45, 7
	s_add_u32 s59, s59, s78
	s_add_u32 s80, s4, s59
	s_addc_u32 s81, s5, 0
	v_mul_u32_u24_e32 v142, s57, v132
	v_lshl_add_u32 v142, v133, 1, v142
	s_waitcnt lgkmcnt(0)
	s_barrier
	s_lshl_b32 s78, s52, 2
	s_cmp_lt_u32 s78, s58
	s_cbranch_scc0 .Lcv1_t1_0_end
	s_lshl_b32 s78, s78, 6
	ds_read_b32 v144, v135 offset:0
	ds_read_b32 v145, v135 offset:260
	ds_read_b32 v146, v135 offset:520
	ds_read_b32 v147, v135 offset:780
	ds_read_b32 v148, v135 offset:1040
	ds_read_b32 v149, v135 offset:1300
	ds_read_b32 v150, v135 offset:1560
	ds_read_b32 v151, v135 offset:1820
	s_mov_b32 s18, 1
	s_mov_b32 s98, 0
	s_mov_b32 s45, 0
	s_mov_b32 s99, 0
	s_cmp_eq_u32 s56, 3
	s_cbranch_scc1 .Lcv1_t1_0_win
	s_lshr_b32 s79, s78, 7
	s_lshl_b32 s79, s79, 8
	s_and_b32 s59, s78, 0x7f
	s_add_u32 s59, s79, s59
	s_cmp_eq_u32 s56, 0
	s_cselect_b32 s79, s78, s59
	s_cmp_eq_u32 s56, 2
	s_cselect_b32 s59, 0x80, 0
	s_add_u32 s79, s79, s59
	s_branch .Lcv1_t1_0_map
.Lcv1_t1_0_win:
	s_sub_u32 s99, 0xb08, s78
	s_max_i32 s99, s99, 0
	s_movk_i32 s59, 0x308
	s_mov_b32 s97, 0
	s_cmp_lt_u32 s78, 0xb00
	s_cselect_b32 s18, 1, s18
	s_cselect_b32 s98, 0, s98
	s_cselect_b32 s99, 0, s99
	s_cselect_b32 s59, 0x300, s59
	s_cselect_b32 s97, 0x0, s97
	s_cmp_lt_u32 s78, 0xa00
	s_cselect_b32 s18, 1, s18
	s_cselect_b32 s98, 1, s98
	s_cselect_b32 s99, 0, s99
	s_cselect_b32 s59, 0x300, s59
	s_cselect_b32 s97, 0x1200, s97
	s_cmp_lt_u32 s78, 0x900
	s_cselect_b32 s18, 0, s18
	s_cselect_b32 s98, 1, s98
	s_cselect_b32 s99, 0, s99
	s_cselect_b32 s59, 0x0, s59
	s_cselect_b32 s97, 0x1200, s97
	s_cmp_lt_u32 s78, 0x800
	s_cselect_b32 s18, 1, s18
	s_cselect_b32 s98, 0, s98
	s_cselect_b32 s99, 0, s99
	s_cselect_b32 s59, 0x200, s59
	s_cselect_b32 s97, 0x0, s97
	s_cmp_lt_u32 s78, 0x700
	s_cselect_b32 s18, 0, s18
	s_cselect_b32 s98, 1, s98
	s_cselect_b32 s99, 0, s99
	s_cselect_b32 s59, 0x0, s59
	s_cselect_b32 s97, 0x1300, s97
	s_cmp_lt_u32 s78, 0x680
	s_cselect_b32 s18, 1, s18
	s_cselect_b32 s98, 0, s98
	s_cselect_b32 s99, 0, s99
	s_cselect_b32 s59, 0x180, s59
	s_cselect_b32 s97, 0x0, s97
	s_cmp_lt_u32 s78, 0x500
	s_cselect_b32 s18, 0, s18
	s_cselect_b32 s98, 1, s98
	s_cselect_b32 s99, 0, s99
	s_cselect_b32 s59, 0x0, s59
	s_cselect_b32 s97, 0x1480, s97
	s_cmp_lt_u32 s78, 0x400
	s_cselect_b32 s18, 1, s18
	s_cselect_b32 s98, 0, s98
	s_cselect_b32 s99, 0, s99
	s_cselect_b32 s59, 0x80, s59
	s_cselect_b32 s97, 0x0, s97
	s_cmp_lt_u32 s78, 0x200
	s_cselect_b32 s18, 0, s18
	s_cselect_b32 s98, 1, s98
	s_cselect_b32 s99, 0, s99
	s_cselect_b32 s59, 0x0, s59
	s_cselect_b32 s97, 0x1680, s97
	s_cmp_lt_u32 s78, 0x180
	s_cselect_b32 s18, 1, s18
	s_cselect_b32 s98, 0, s98
	s_cselect_b32 s99, 0, s99
	s_cselect_b32 s59, 0x0, s59
	s_cselect_b32 s97, 0x0, s97
	s_sub_u32 s79, s78, s59
	s_add_u32 s45, s78, s97
.Lcv1_t1_0_map:
	s_sub_i32 s59, s100, s78
	v_cmp_le_i32_e32 vcc, s99, v132
	s_mov_b32 s99, s79
	v_cmp_gt_i32_e64 s[78:79], s59, v132
	s_waitcnt lgkmcnt(0)
	v_cvt_pk_bf16_f32 v152, v144, v145
	v_cvt_pk_bf16_f32 v153, v146, v147
	v_cvt_pk_bf16_f32 v154, v148, v149
	v_cvt_pk_bf16_f32 v155, v150, v151
	s_and_b64 exec, vcc, s[78:79]
	s_cbranch_execz .Lcv1_t1_0_skip
	s_cmp_eq_u32 s18, 0
	s_cbranch_scc1 .Lcv1_t1_0_no1
	s_mul_i32 s59, s99, s57
	s_add_u32 s78, s80, s59
	s_addc_u32 s79, s81, 0
	global_store_dwordx4 v142, v[152:155], s[78:79]
.Lcv1_t1_0_no1:
	s_cmp_eq_u32 s98, 0
	s_cbranch_scc1 .Lcv1_t1_0_skip
	s_mul_i32 s59, s45, s57
	s_add_u32 s78, s80, s59
	s_addc_u32 s79, s81, 0
	global_store_dwordx4 v142, v[152:155], s[78:79]

.Lcv1_t1_0_end:
	s_lshl_b32 s78, s52, 2
	s_add_u32 s78, s78, 1
	s_cmp_lt_u32 s78, s58
	s_cbranch_scc0 .Lcv1_t1_1_end
	s_lshl_b32 s78, s78, 6
	ds_read_b32 v144, v135 offset:16640
	ds_read_b32 v145, v135 offset:16900
	ds_read_b32 v146, v135 offset:17160
	ds_read_b32 v147, v135 offset:17420
	ds_read_b32 v148, v135 offset:17680
	ds_read_b32 v149, v135 offset:17940
	ds_read_b32 v150, v135 offset:18200
	ds_read_b32 v151, v135 offset:18460
	s_mov_b32 s18, 1
	s_mov_b32 s98, 0
	s_mov_b32 s45, 0
	s_mov_b32 s99, 0
	s_cmp_eq_u32 s56, 3
	s_cbranch_scc1 .Lcv1_t1_1_win
	s_lshr_b32 s79, s78, 7
	s_lshl_b32 s79, s79, 8
	s_and_b32 s59, s78, 0x7f
	s_add_u32 s59, s79, s59
	s_cmp_eq_u32 s56, 0
	s_cselect_b32 s79, s78, s59
	s_cmp_eq_u32 s56, 2
	s_cselect_b32 s59, 0x80, 0
	s_add_u32 s79, s79, s59
	s_branch .Lcv1_t1_1_map

.Lcv1_t1_1_end:
	s_lshl_b32 s78, s52, 2
	s_add_u32 s78, s78, 2
	s_cmp_lt_u32 s78, s58
	s_cbranch_scc0 .Lcv1_t1_2_end
	s_lshl_b32 s78, s78, 6
	ds_read_b32 v144, v135 offset:33280
	ds_read_b32 v145, v135 offset:33540
	ds_read_b32 v146, v135 offset:33800
	ds_read_b32 v147, v135 offset:34060
	ds_read_b32 v148, v135 offset:34320
	ds_read_b32 v149, v135 offset:34580
	ds_read_b32 v150, v135 offset:34840
	ds_read_b32 v151, v135 offset:35100
	s_mov_b32 s18, 1
	s_mov_b32 s98, 0
	s_mov_b32 s45, 0
	s_mov_b32 s99, 0
	s_cmp_eq_u32 s56, 3
	s_cbranch_scc1 .Lcv1_t1_2_win
	s_lshr_b32 s79, s78, 7
	s_lshl_b32 s79, s79, 8
	s_and_b32 s59, s78, 0x7f
	s_add_u32 s59, s79, s59
	s_cmp_eq_u32 s56, 0
	s_cselect_b32 s79, s78, s59
	s_cmp_eq_u32 s56, 2
	s_cselect_b32 s59, 0x80, 0
	s_add_u32 s79, s79, s59
	s_branch .Lcv1_t1_2_map

.Lcv1_t1_2_end:
	s_lshl_b32 s78, s52, 2
	s_add_u32 s78, s78, 3
	s_cmp_lt_u32 s78, s58
	s_cbranch_scc0 .Lcv1_t1_3_end
	s_lshl_b32 s78, s78, 6
	ds_read_b32 v144, v135 offset:49920
	ds_read_b32 v145, v135 offset:50180
	ds_read_b32 v146, v135 offset:50440
	ds_read_b32 v147, v135 offset:50700
	ds_read_b32 v148, v135 offset:50960
	ds_read_b32 v149, v135 offset:51220
	ds_read_b32 v150, v135 offset:51480
	ds_read_b32 v151, v135 offset:51740
	s_mov_b32 s18, 1
	s_mov_b32 s98, 0
	s_mov_b32 s45, 0
	s_mov_b32 s99, 0
	s_cmp_eq_u32 s56, 3
	s_cbranch_scc1 .Lcv1_t1_3_win
	s_lshr_b32 s79, s78, 7
	s_lshl_b32 s79, s79, 8
	s_and_b32 s59, s78, 0x7f
	s_add_u32 s59, s79, s59
	s_cmp_eq_u32 s56, 0
	s_cselect_b32 s79, s78, s59
	s_cmp_eq_u32 s56, 2
	s_cselect_b32 s59, 0x80, 0
	s_add_u32 s79, s79, s59
	s_branch .Lcv1_t1_3_map

.Lcv1_t1_3_end:
	s_barrier
	s_cmp_lt_u32 s96, s90
	s_cbranch_scc0 .Lcv1_ret
	s_mov_b32 s93, s96
	s_add_u32 s96, s93, s95
	s_cmp_lt_u32 s96, s90
	s_cbranch_scc0 .Lcv1_last1
	s_mov_b32 s97, 0
	s_mov_b32 s56, 0
	s_cmp_ge_u32 s96, 176
	s_cselect_b32 s97, 1, s97
	s_cselect_b32 s56, 176, s56
	s_cmp_ge_u32 s96, 352
	s_cselect_b32 s97, 2, s97
	s_cselect_b32 s56, 352, s56
	s_cmp_ge_u32 s96, 528
	s_cselect_b32 s97, 3, s97
	s_cselect_b32 s56, 528, s56
	s_cmp_ge_u32 s96, 976
	s_cselect_b32 s97, 4, s97
	s_cselect_b32 s56, 976, s56
	s_cmp_ge_u32 s96, 1040
	s_cselect_b32 s97, 5, s97
	s_cselect_b32 s56, 1040, s56
	s_cmp_ge_u32 s96, 1104
	s_cselect_b32 s97, 6, s97
	s_cselect_b32 s56, 1104, s56
	s_cmp_ge_u32 s96, 1280
	s_cselect_b32 s97, 7, s97
	s_cselect_b32 s56, 1280, s56
	s_cmp_ge_u32 s96, 1456
	s_cselect_b32 s97, 8, s97
	s_cselect_b32 s56, 1456, s56
	s_sub_u32 s98, s96, s56
	s_and_b32 s56, s98, 15
	s_lshr_b32 s57, s98, 4
	s_cmp_eq_u32 s97, 4
	s_cselect_b32 s99, s57, 0
	s_cselect_b32 s98, s56, s98
	s_movk_i32 s100, 0x400
	s_mov_b32 s18, 4
	s_movk_i32 s57, 0x4000
	s_mov_b32 s58, 16
	s_movk_i32 s59, 0xc3
	s_bitcmp1_b32 s59, s97
	s_cselect_b32 s100, 0xb00, s100
	s_cselect_b32 s18, 11, s18
	s_cselect_b32 s57, 0x1746, s57
	s_cselect_b32 s58, 44, s58
	s_cmp_eq_u32 s97, 3
	s_cselect_b32 s100, 0x1b08, s100
	s_cselect_b32 s18, 28, s18
	s_cselect_b32 s57, 0x925, s57
	s_cselect_b32 s58, 0x6d, s58
	s_mul_i32 s45, s98, s57
	s_lshr_b32 s45, s45, 16
	s_mul_i32 s59, s45, s18
	s_sub_u32 s52, s98, s59
	s_mov_b32 s56, 0xb00000
	s_cmp_eq_u32 s97, 3
	s_cselect_b32 s56, 0x1b08000, s56
	s_cmp_eq_u32 s97, 5
	s_cselect_b32 s56, 0x400000, s56
	s_cmp_eq_u32 s97, 4
	s_cselect_b32 s56, 0x400000, s56
	s_mul_i32 s56, s56, s92
	s_lshl_b32 s59, s99, 20
	s_add_u32 s56, s56, s59
	s_mul_i32 s59, s45, s100
	s_lshl_b32 s59, s59, 8
	s_add_u32 s56, s56, s59
	s_lshl_b32 s59, s52, 10
	s_add_u32 s56, s56, s59
	s_mov_b64 s[78:79], s[6:7]
	s_cmp_eq_u32 s97, 1
	s_cselect_b32 s78, s8, s78
	s_cselect_b32 s79, s9, s79
	s_cmp_eq_u32 s97, 2
	s_cselect_b32 s78, s20, s78
	s_cselect_b32 s79, s21, s79
	s_cmp_eq_u32 s97, 3
	s_cselect_b32 s78, s34, s78
	s_cselect_b32 s79, s35, s79
	s_cmp_eq_u32 s97, 4
	s_cselect_b32 s78, s40, s78
	s_cselect_b32 s79, s41, s79
	s_cmp_eq_u32 s97, 5
	s_cselect_b32 s78, s42, s78
	s_cselect_b32 s79, s43, s79
	s_cmp_eq_u32 s97, 6
	s_cselect_b32 s78, s46, s78
	s_cselect_b32 s79, s47, s79
	s_cmp_eq_u32 s97, 7
	s_cselect_b32 s78, s48, s78
	s_cselect_b32 s79, s49, s79
	s_cmp_eq_u32 s97, 8
	s_cselect_b32 s78, s50, s78
	s_cselect_b32 s79, s51, s79
	s_add_u32 s78, s78, s56
	s_addc_u32 s79, s79, 0
	s_lshl_b32 s59, s100, 2
	v_mul_u32_u24_e32 v141, s59, v132
	v_lshl_add_u32 v141, v133, 2, v141
	s_lshl_b32 s80, s52, 2
	s_cmp_lt_u32 s80, s58
	s_cselect_b32 s81, 0, 0
	s_lshl_b32 s80, s52, 8
	s_add_u32 s80, s80, s81
	s_sub_i32 s80, s100, s80
	s_sub_i32 s80, s80, 8
	v_cmp_ge_i32_e32 vcc, s80, v133
	s_mov_b64 exec, vcc
	s_lshl_b32 s81, s81, 2
	s_add_u32 s56, s78, s81
	s_addc_u32 s57, s79, 0
	global_load_dwordx4 v[100:103], v141, s[56:57]
	global_load_dwordx4 v[104:107], v141, s[56:57] offset:16
	s_lshl_b32 s80, s52, 2
	s_add_u32 s80, s80, 1
	s_cmp_lt_u32 s80, s58
	s_cselect_b32 s81, 64, 0
	s_lshl_b32 s80, s52, 8
	s_add_u32 s80, s80, s81
	s_sub_i32 s80, s100, s80
	s_sub_i32 s80, s80, 8
	v_cmp_ge_i32_e32 vcc, s80, v133
	s_mov_b64 exec, vcc
	s_lshl_b32 s81, s81, 2
	s_add_u32 s56, s78, s81
	s_addc_u32 s57, s79, 0
	global_load_dwordx4 v[108:111], v141, s[56:57]
	global_load_dwordx4 v[112:115], v141, s[56:57] offset:16
	s_lshl_b32 s80, s52, 2
	s_add_u32 s80, s80, 2
	s_cmp_lt_u32 s80, s58
	s_cselect_b32 s81, 128, 0
	s_lshl_b32 s80, s52, 8
	s_add_u32 s80, s80, s81
	s_sub_i32 s80, s100, s80
	s_sub_i32 s80, s80, 8
	v_cmp_ge_i32_e32 vcc, s80, v133
	s_mov_b64 exec, vcc
	s_lshl_b32 s81, s81, 2
	s_add_u32 s56, s78, s81
	s_addc_u32 s57, s79, 0
	global_load_dwordx4 v[116:119], v141, s[56:57]
	global_load_dwordx4 v[120:123], v141, s[56:57] offset:16
	s_lshl_b32 s80, s52, 2
	s_add_u32 s80, s80, 3
	s_cmp_lt_u32 s80, s58
	s_cselect_b32 s81, 192, 0
	s_lshl_b32 s80, s52, 8
	s_add_u32 s80, s80, s81
	s_sub_i32 s80, s100, s80
	s_sub_i32 s80, s80, 8
	v_cmp_ge_i32_e32 vcc, s80, v133
	s_mov_b64 exec, vcc
	s_lshl_b32 s81, s81, 2
	s_add_u32 s56, s78, s81
	s_addc_u32 s57, s79, 0
	global_load_dwordx4 v[124:127], v141, s[56:57]
	global_load_dwordx4 v[128:131], v141, s[56:57] offset:16
	s_mov_b64 exec, -1
	s_waitcnt vmcnt(8)
	s_branch .Lcv1_go1

.Lcv1_go1:
	ds_write_b32 v134, v168 offset:0
	ds_write_b32 v134, v169 offset:4
	ds_write_b32 v134, v170 offset:8
	ds_write_b32 v134, v171 offset:12
	ds_write_b32 v134, v172 offset:16
	ds_write_b32 v134, v173 offset:20
	ds_write_b32 v134, v174 offset:24
	ds_write_b32 v134, v175 offset:28
	ds_write_b32 v134, v176 offset:16640
	ds_write_b32 v134, v177 offset:16644
	ds_write_b32 v134, v178 offset:16648
	ds_write_b32 v134, v179 offset:16652
	ds_write_b32 v134, v180 offset:16656
	ds_write_b32 v134, v181 offset:16660
	ds_write_b32 v134, v182 offset:16664
	ds_write_b32 v134, v183 offset:16668
	ds_write_b32 v134, v184 offset:33280
	ds_write_b32 v134, v185 offset:33284
	ds_write_b32 v134, v186 offset:33288
	ds_write_b32 v134, v187 offset:33292
	ds_write_b32 v134, v188 offset:33296
	ds_write_b32 v134, v189 offset:33300
	ds_write_b32 v134, v190 offset:33304
	ds_write_b32 v134, v191 offset:33308
	ds_write_b32 v134, v192 offset:49920
	ds_write_b32 v134, v193 offset:49924
	ds_write_b32 v134, v194 offset:49928
	ds_write_b32 v134, v195 offset:49932
	ds_write_b32 v134, v196 offset:49936
	ds_write_b32 v134, v197 offset:49940
	ds_write_b32 v134, v198 offset:49944
	ds_write_b32 v134, v199 offset:49948
	s_mov_b32 s97, 0
	s_mov_b32 s56, 0
	s_cmp_ge_u32 s93, 176
	s_cselect_b32 s97, 1, s97
	s_cselect_b32 s56, 176, s56
	s_cmp_ge_u32 s93, 352
	s_cselect_b32 s97, 2, s97
	s_cselect_b32 s56, 352, s56
	s_cmp_ge_u32 s93, 528
	s_cselect_b32 s97, 3, s97
	s_cselect_b32 s56, 528, s56
	s_cmp_ge_u32 s93, 976
	s_cselect_b32 s97, 4, s97
	s_cselect_b32 s56, 976, s56
	s_cmp_ge_u32 s93, 1040
	s_cselect_b32 s97, 5, s97
	s_cselect_b32 s56, 1040, s56
	s_cmp_ge_u32 s93, 1104
	s_cselect_b32 s97, 6, s97
	s_cselect_b32 s56, 1104, s56
	s_cmp_ge_u32 s93, 1280
	s_cselect_b32 s97, 7, s97
	s_cselect_b32 s56, 1280, s56
	s_cmp_ge_u32 s93, 1456
	s_cselect_b32 s97, 8, s97
	s_cselect_b32 s56, 1456, s56
	s_sub_u32 s98, s93, s56
	s_and_b32 s56, s98, 15
	s_lshr_b32 s57, s98, 4
	s_cmp_eq_u32 s97, 4
	s_cselect_b32 s99, s57, 0
	s_cselect_b32 s98, s56, s98
	s_movk_i32 s100, 0x400
	s_mov_b32 s18, 4
	s_movk_i32 s57, 0x4000
	s_mov_b32 s58, 16
	s_movk_i32 s59, 0xc3
	s_bitcmp1_b32 s59, s97
	s_cselect_b32 s100, 0xb00, s100
	s_cselect_b32 s18, 11, s18
	s_cselect_b32 s57, 0x1746, s57
	s_cselect_b32 s58, 44, s58
	s_cmp_eq_u32 s97, 3
	s_cselect_b32 s100, 0x1b08, s100
	s_cselect_b32 s18, 28, s18
	s_cselect_b32 s57, 0x925, s57
	s_cselect_b32 s58, 0x6d, s58
	s_mul_i32 s45, s98, s57
	s_lshr_b32 s45, s45, 16
	s_mul_i32 s59, s45, s18
	s_sub_u32 s52, s98, s59
	s_mov_b32 s56, 0
	s_movk_i32 s59, 0x41
	s_bitcmp1_b32 s59, s97
	s_cselect_b32 s56, 1, s56
	s_movk_i32 s59, 0x82
	s_bitcmp1_b32 s59, s97
	s_cselect_b32 s56, 2, s56
	s_cmp_eq_u32 s97, 3
	s_cselect_b32 s56, 3, s56
	s_movk_i32 s57, 0x800
	s_movk_i32 s59, 0x104
	s_bitcmp1_b32 s59, s97
	s_cselect_b32 s57, 0x1600, s57
	s_mov_b32 s59, 0
	s_cmp_eq_u32 s97, 2
	s_cselect_b32 s59, 0xb00000, s59
	s_cmp_eq_u32 s97, 3
	s_cselect_b32 s59, 0x1080000, s59
	s_cmp_eq_u32 s97, 4
	s_cselect_b32 s59, 0x1e80000, s59
	s_cmp_eq_u32 s97, 5
	s_cselect_b32 s59, 0x2080000, s59
	s_cmp_eq_u32 s97, 6
	s_cselect_b32 s59, 0x2280000, s59
	s_cmp_eq_u32 s97, 7
	s_cselect_b32 s59, 0x2280000, s59
	s_cmp_eq_u32 s97, 8
	s_cselect_b32 s59, 0x2d80000, s59
	s_lshl_b32 s78, s99, 9
	s_add_u32 s59, s59, s78
	s_lshl_b32 s78, s45, 7
	s_add_u32 s59, s59, s78
	s_add_u32 s80, s4, s59
	s_addc_u32 s81, s5, 0
	v_mul_u32_u24_e32 v142, s57, v132
	v_lshl_add_u32 v142, v133, 1, v142
	s_waitcnt lgkmcnt(0)
	s_barrier
	s_lshl_b32 s78, s52, 2
	s_cmp_lt_u32 s78, s58
	s_cbranch_scc0 .Lcv1_t2_0_end
	s_lshl_b32 s78, s78, 6
	ds_read_b32 v144, v135 offset:0
	ds_read_b32 v145, v135 offset:260
	ds_read_b32 v146, v135 offset:520
	ds_read_b32 v147, v135 offset:780
	ds_read_b32 v148, v135 offset:1040
	ds_read_b32 v149, v135 offset:1300
	ds_read_b32 v150, v135 offset:1560
	ds_read_b32 v151, v135 offset:1820
	s_mov_b32 s18, 1
	s_mov_b32 s98, 0
	s_mov_b32 s45, 0
	s_mov_b32 s99, 0
	s_cmp_eq_u32 s56, 3
	s_cbranch_scc1 .Lcv1_t2_0_win
	s_lshr_b32 s79, s78, 7
	s_lshl_b32 s79, s79, 8
	s_and_b32 s59, s78, 0x7f
	s_add_u32 s59, s79, s59
	s_cmp_eq_u32 s56, 0
	s_cselect_b32 s79, s78, s59
	s_cmp_eq_u32 s56, 2
	s_cselect_b32 s59, 0x80, 0
	s_add_u32 s79, s79, s59
	s_branch .Lcv1_t2_0_map

.Lcv1_t2_3_end:
	s_barrier
	s_cmp_lt_u32 s96, s90
	s_cbranch_scc0 .Lcv1_ret
	s_mov_b32 s93, s96
	s_branch .Lcv1_loop
.Lcv1_ret:
	s_waitcnt vmcnt(0) lgkmcnt(0)
	s_branch .LBB0_345


.LBB0_1792:
	s_and_b64 vcc, exec, s[6:7]
	s_cbranch_vccz .LBB0_2359
	s_and_b64 vcc, exec, s[38:39]
	s_cbranch_vccnz .LBB0_2046
	v_readlane_b32 s92, v254, 38
	s_mov_b32 s89, 0
	s_movk_i32 s90, 0x3d0
	s_mov_b32 s91, 48
	s_mov_b32 s101, 2
	s_add_u32 s92, s92, 1
	s_branch .Lcv2_entry
	v_mov_b32_e32 v0, s64
	v_mov_b32_e32 v2, s65
	s_nop 0
	v_readfirstlane_b32 s0, v0
	v_readfirstlane_b32 s1, v2
	v_mov_b32_e32 v0, s88
	v_mov_b32_e32 v2, s0
	v_mov_b32_e32 v3, s1
	global_load_dwordx2 v[2:3], v[2:3], off offset:248
	s_waitcnt vmcnt(0) lgkmcnt(0)
	s_nop 0
	v_readfirstlane_b32 s4, v0
	v_readfirstlane_b32 s0, v2
	s_cmp_lt_i32 s4, 48
	v_readfirstlane_b32 s1, v3
	s_cbranch_scc1 .LBB0_2046
	s_sub_i32 s4, s4, 48
	s_cmpk_gt_u32 s4, 0x3cf
	s_cbranch_scc1 .LBB0_2046
	s_add_u32 s5, s0, 0x1080000
	s_addc_u32 s20, s1, 0
	s_add_u32 s21, s0, 0xb00000
	v_readlane_b32 s6, v254, 21
	s_addc_u32 s33, s1, 0
	s_lshl_b32 s34, s4, 8
	s_lshl_b32 s35, s6, 8
	s_lshl_b32 s44, s4, 4
	s_lshl_b32 s45, s6, 4
	s_branch .LBB0_1799

.Lcv2_ret:
	s_waitcnt vmcnt(0) lgkmcnt(0)
	s_cmp_eq_u32 s101, 2
	s_cbranch_scc1 .LBB0_2046
	s_branch .LBB0_2359


.LBB0_2046:
	v_readlane_b32 s0, v255, 0
	v_readlane_b32 s4, v255, 8
	v_readlane_b32 s1, v255, 1
	v_readlane_b32 s5, v255, 9
	s_and_b64 s[0:1], s[0:1], s[4:5]
	s_andn2_b64 vcc, exec, s[0:1]
	s_cbranch_vccnz .LBB0_2359
	v_readlane_b32 s92, v254, 38
	s_movk_i32 s89, 0x3d0
	s_movk_i32 s90, 0x660
	s_mov_b32 s91, 48
	s_mov_b32 s101, 3
	s_branch .Lcv2_entry
	v_mov_b32_e32 v0, s64
	v_mov_b32_e32 v2, s65
	s_nop 0
	v_readfirstlane_b32 s0, v0
	v_readfirstlane_b32 s1, v2
	v_mov_b32_e32 v0, s88
	v_mov_b32_e32 v2, s0
	v_mov_b32_e32 v3, s1
	global_load_dwordx2 v[2:3], v[2:3], off offset:248
	s_waitcnt vmcnt(0) lgkmcnt(0)
	s_nop 0
	v_readfirstlane_b32 s4, v0
	v_readfirstlane_b32 s0, v2
	s_cmp_lt_i32 s4, 48
	v_readfirstlane_b32 s1, v3
	s_cbranch_scc1 .LBB0_2359
	s_addk_i32 s4, 0x3a0
	s_cmpk_gt_i32 s4, 0x65f
	s_cbranch_scc1 .LBB0_2359
	s_add_u32 s5, s0, 0x2d80000
	s_addc_u32 s20, s1, 0
	s_add_u32 s21, s0, 0x2280000
	s_addc_u32 s33, s1, 0
	s_add_u32 s34, s0, 0x2080000
	s_addc_u32 s35, s1, 0
	s_add_u32 s44, s0, 0x1e80000
	s_addc_u32 s45, s1, 0
	s_add_u32 s46, s0, 0x1080000
	s_addc_u32 s47, s1, 0
	s_add_u32 s48, s0, 0xb00000
	v_readlane_b32 s6, v254, 21
	s_addc_u32 s49, s1, 0
	s_lshl_b32 s50, s4, 8
	s_lshl_b32 s51, s6, 8
	s_lshl_b32 s52, s4, 4
	s_lshl_b32 s53, s6, 4
	s_branch .LBB0_2052
